# NSA stream softmax: 32 v_sub + 32 v_add per tile replaced by 16+16 v_pk_add_f32 (f32 packed), temps in free v220-v251
# baseline (speedup 1.0000x reference)
; DI float half_max(float x) { float a, b; half_swap(x, a, b); return fmaxf(a, b); }
; DI float ex2(float x) { return __builtin_amdgcn_exp2f(x); }
; template <bool HAS_O>
; DI void softmax_finish(f32x16 (&S)[2], float mx, float cbias, float& m, float& l, f32x16 (&O)[2]) {
;   mx = half_max(mx);
;   const float mn = (mx > m + 8.f) ? mx : m;
;   const float alpha = ex2(m - mn);
;   m = mn;
;   const float c = mn + cbias;
;   float sum = 0.f;
; #pragma unroll
;   for (int kt2 = 0; kt2 < 2; ++kt2)
; #pragma unroll
;     for (int e = 0; e < 16; ++e) { const float pv = ex2(S[kt2][e] - c); S[kt2][e] = pv; sum += pv; }
;   l = l * alpha + sum;
;   if constexpr (HAS_O) {
;     if (__ballot(alpha != 1.f) != 0ull) {
; template <bool HAS_O>
; DI void softmax_fast(f32x16 (&S)[2], float& m, float& l, f32x16 (&O)[2], bool live) {
;   float mx = S[0][0];
; #pragma unroll
;   for (int kt2 = 0; kt2 < 2; ++kt2)
; #pragma unroll
;     for (int e = 0; e < 16; ++e) mx = fmaxf(mx, S[kt2][e]);
;   softmax_finish<HAS_O>(S, live ? mx : -1e30f, live ? 0.f : 1e30f, m, l, O);
; }
.LBB0_950:
	v_max_f32_e32 v0, v65, v65
	v_max_f32_e32 v2, v64, v64
	v_max_f32_e32 v0, v2, v0
	v_max3_f32 v0, v0, v66, v67
	v_max3_f32 v0, v0, v68, v69
	v_max3_f32 v0, v0, v70, v71
	v_max3_f32 v0, v0, v72, v73
	v_max3_f32 v0, v0, v74, v75
	v_max3_f32 v0, v0, v76, v77
	v_max3_f32 v0, v0, v78, v79
	v_max3_f32 v0, v0, v48, v49
	v_max3_f32 v0, v0, v50, v51
	v_max3_f32 v0, v0, v52, v53
	v_max3_f32 v0, v0, v54, v55
	v_max3_f32 v0, v0, v56, v57
	v_max3_f32 v0, v0, v58, v59
	v_max3_f32 v0, v0, v60, v61
	v_max3_f32 v0, v0, v62, v63
	v_mov_b32_e32 v2, v0
	s_nop 1
	v_permlane32_swap_b32_e32 v0, v2
	v_max_f32_e32 v2, v2, v2
	v_max_f32_e32 v0, v0, v0
	v_max_f32_e32 v0, v0, v2
	v_add_f32_e32 v2, 0x41000000, v208
	v_cmp_gt_f32_e32 vcc, v0, v2
	s_nop 1
	v_cndmask_b32_e32 v209, v208, v0, vcc
	v_add_f32_e32 v0, 0, v209
	v_pk_add_f32 v[220:221], v[64:65], v[0:1] op_sel_hi:[1,0] neg_lo:[0,1] neg_hi:[0,1]
	v_pk_add_f32 v[222:223], v[66:67], v[0:1] op_sel_hi:[1,0] neg_lo:[0,1] neg_hi:[0,1]
	v_sub_f32_e32 v4, v208, v209
	v_exp_f32_e32 v80, v220
	v_pk_add_f32 v[224:225], v[68:69], v[0:1] op_sel_hi:[1,0] neg_lo:[0,1] neg_hi:[0,1]
	v_exp_f32_e32 v81, v221
	v_exp_f32_e32 v82, v222
	v_pk_add_f32 v[226:227], v[70:71], v[0:1] op_sel_hi:[1,0] neg_lo:[0,1] neg_hi:[0,1]
	v_exp_f32_e32 v83, v223
	v_exp_f32_e32 v84, v224
	v_pk_add_f32 v[228:229], v[72:73], v[0:1] op_sel_hi:[1,0] neg_lo:[0,1] neg_hi:[0,1]
	v_exp_f32_e32 v85, v225
	v_pk_add_f32 v[2:3], v[80:81], v[82:83]
	v_exp_f32_e32 v86, v226
	v_pk_add_f32 v[230:231], v[74:75], v[0:1] op_sel_hi:[1,0] neg_lo:[0,1] neg_hi:[0,1]
	v_exp_f32_e32 v87, v227
	v_pk_add_f32 v[2:3], v[2:3], v[84:85]
	v_exp_f32_e32 v88, v228
	v_pk_add_f32 v[232:233], v[76:77], v[0:1] op_sel_hi:[1,0] neg_lo:[0,1] neg_hi:[0,1]
	v_exp_f32_e32 v89, v229
	v_pk_add_f32 v[2:3], v[2:3], v[86:87]
	v_exp_f32_e32 v90, v230
	v_pk_add_f32 v[234:235], v[78:79], v[0:1] op_sel_hi:[1,0] neg_lo:[0,1] neg_hi:[0,1]
	v_exp_f32_e32 v91, v231
	v_pk_add_f32 v[2:3], v[2:3], v[88:89]
	v_exp_f32_e32 v92, v232
	v_pk_add_f32 v[236:237], v[48:49], v[0:1] op_sel_hi:[1,0] neg_lo:[0,1] neg_hi:[0,1]
	v_exp_f32_e32 v93, v233
	v_pk_add_f32 v[2:3], v[2:3], v[90:91]
	v_exp_f32_e32 v94, v234
	v_pk_add_f32 v[238:239], v[50:51], v[0:1] op_sel_hi:[1,0] neg_lo:[0,1] neg_hi:[0,1]
	v_exp_f32_e32 v95, v235
	v_pk_add_f32 v[2:3], v[2:3], v[92:93]
	v_exp_f32_e32 v96, v236
	v_pk_add_f32 v[240:241], v[52:53], v[0:1] op_sel_hi:[1,0] neg_lo:[0,1] neg_hi:[0,1]
	v_exp_f32_e32 v97, v237
	v_pk_add_f32 v[2:3], v[2:3], v[94:95]
	v_exp_f32_e32 v98, v238
	v_pk_add_f32 v[242:243], v[54:55], v[0:1] op_sel_hi:[1,0] neg_lo:[0,1] neg_hi:[0,1]
	v_exp_f32_e32 v99, v239
	v_pk_add_f32 v[2:3], v[2:3], v[96:97]
	v_exp_f32_e32 v100, v240
	v_pk_add_f32 v[244:245], v[56:57], v[0:1] op_sel_hi:[1,0] neg_lo:[0,1] neg_hi:[0,1]
	v_exp_f32_e32 v101, v241
	v_pk_add_f32 v[2:3], v[2:3], v[98:99]
	v_exp_f32_e32 v102, v242
	v_pk_add_f32 v[246:247], v[58:59], v[0:1] op_sel_hi:[1,0] neg_lo:[0,1] neg_hi:[0,1]
	v_exp_f32_e32 v103, v243
	v_pk_add_f32 v[2:3], v[2:3], v[100:101]
	v_exp_f32_e32 v104, v244
	v_pk_add_f32 v[248:249], v[60:61], v[0:1] op_sel_hi:[1,0] neg_lo:[0,1] neg_hi:[0,1]
	v_exp_f32_e32 v105, v245
	v_pk_add_f32 v[2:3], v[2:3], v[102:103]
	v_exp_f32_e32 v106, v246
	v_pk_add_f32 v[250:251], v[62:63], v[0:1] op_sel_hi:[1,0] neg_lo:[0,1] neg_hi:[0,1]
	v_exp_f32_e32 v107, v247
	v_pk_add_f32 v[2:3], v[2:3], v[104:105]
	v_exp_f32_e32 v108, v248
	v_exp_f32_e32 v109, v249
	v_pk_add_f32 v[2:3], v[2:3], v[106:107]
	v_exp_f32_e32 v110, v250
	v_exp_f32_e32 v111, v251
	v_pk_add_f32 v[2:3], v[2:3], v[108:109]
	v_exp_f32_e32 v0, v4
	v_pk_add_f32 v[2:3], v[2:3], v[110:111]
	v_cmp_neq_f32_e32 vcc, 1.0, v0
	v_add_f32_e32 v213, v2, v3
	s_cmp_lg_u64 vcc, 0
	v_fmac_f32_e32 v213, v149, v0
	s_cselect_b64 s[0:1], -1, 0

; DI float half_max(float x) { float a, b; half_swap(x, a, b); return fmaxf(a, b); }
; DI float ex2(float x) { return __builtin_amdgcn_exp2f(x); }
; template <bool HAS_O>
; DI void softmax_finish(f32x16 (&S)[2], float mx, float cbias, float& m, float& l, f32x16 (&O)[2]) {
;   mx = half_max(mx);
;   const float mn = (mx > m + 8.f) ? mx : m;
;   const float alpha = ex2(m - mn);
;   m = mn;
;   const float c = mn + cbias;
;   float sum = 0.f;
; #pragma unroll
;   for (int kt2 = 0; kt2 < 2; ++kt2)
; #pragma unroll
;     for (int e = 0; e < 16; ++e) { const float pv = ex2(S[kt2][e] - c); S[kt2][e] = pv; sum += pv; }
;   l = l * alpha + sum;
;   if constexpr (HAS_O) {
;     if (__ballot(alpha != 1.f) != 0ull) {
; template <bool HAS_O>
; DI void softmax_fast(f32x16 (&S)[2], float& m, float& l, f32x16 (&O)[2], bool live) {
;   float mx = S[0][0];
; #pragma unroll
;   for (int kt2 = 0; kt2 < 2; ++kt2)
; #pragma unroll
;     for (int e = 0; e < 16; ++e) mx = fmaxf(mx, S[kt2][e]);
;   softmax_finish<HAS_O>(S, live ? mx : -1e30f, live ? 0.f : 1e30f, m, l, O);
; }
.LBB0_954:
	s_andn2_b64 vcc, exec, s[40:41]
	s_cbranch_vccnz .LBB0_956
	v_max_f32_e32 v0, v65, v65
	v_max_f32_e32 v3, v64, v64
	v_max_f32_e32 v0, v3, v0
	v_max3_f32 v0, v0, v66, v67
	v_max3_f32 v0, v0, v68, v69
	v_max3_f32 v0, v0, v70, v71
	v_max3_f32 v0, v0, v72, v73
	v_max3_f32 v0, v0, v74, v75
	v_max3_f32 v0, v0, v76, v77
	v_max3_f32 v0, v0, v78, v79
	v_max3_f32 v0, v0, v48, v49
	v_max3_f32 v0, v0, v50, v51
	v_max3_f32 v0, v0, v52, v53
	v_max3_f32 v0, v0, v54, v55
	v_max3_f32 v0, v0, v56, v57
	v_max3_f32 v0, v0, v58, v59
	v_max3_f32 v0, v0, v60, v61
	v_max3_f32 v0, v0, v62, v63
	v_cndmask_b32_e64 v0, v0, v185, s[38:39]
	v_mov_b32_e32 v4, v0
	s_nop 1
	v_permlane32_swap_b32_e32 v0, v4
	v_max_f32_e32 v4, v4, v4
	v_max_f32_e32 v0, v0, v0
	v_max_f32_e32 v0, v0, v4
	v_cmp_gt_f32_e32 vcc, v0, v2
	v_cndmask_b32_e64 v3, 0, v190, s[38:39]
	s_nop 0
	v_cndmask_b32_e32 v209, v208, v0, vcc
	v_add_f32_e32 v0, v3, v209
	v_pk_add_f32 v[220:221], v[64:65], v[0:1] op_sel_hi:[1,0] neg_lo:[0,1] neg_hi:[0,1]
	v_pk_add_f32 v[222:223], v[66:67], v[0:1] op_sel_hi:[1,0] neg_lo:[0,1] neg_hi:[0,1]
	v_sub_f32_e32 v4, v208, v209
	v_exp_f32_e32 v80, v220
	v_pk_add_f32 v[224:225], v[68:69], v[0:1] op_sel_hi:[1,0] neg_lo:[0,1] neg_hi:[0,1]
	v_exp_f32_e32 v81, v221
	v_exp_f32_e32 v82, v222
	v_pk_add_f32 v[226:227], v[70:71], v[0:1] op_sel_hi:[1,0] neg_lo:[0,1] neg_hi:[0,1]
	v_exp_f32_e32 v83, v223
	v_exp_f32_e32 v84, v224
	v_pk_add_f32 v[228:229], v[72:73], v[0:1] op_sel_hi:[1,0] neg_lo:[0,1] neg_hi:[0,1]
	v_exp_f32_e32 v85, v225
	v_pk_add_f32 v[2:3], v[80:81], v[82:83]
	v_exp_f32_e32 v86, v226
	v_pk_add_f32 v[230:231], v[74:75], v[0:1] op_sel_hi:[1,0] neg_lo:[0,1] neg_hi:[0,1]
	v_exp_f32_e32 v87, v227
	v_pk_add_f32 v[2:3], v[2:3], v[84:85]
	v_exp_f32_e32 v88, v228
	v_pk_add_f32 v[232:233], v[76:77], v[0:1] op_sel_hi:[1,0] neg_lo:[0,1] neg_hi:[0,1]
	v_exp_f32_e32 v89, v229
	v_pk_add_f32 v[2:3], v[2:3], v[86:87]
	v_exp_f32_e32 v90, v230
	v_pk_add_f32 v[234:235], v[78:79], v[0:1] op_sel_hi:[1,0] neg_lo:[0,1] neg_hi:[0,1]
	v_exp_f32_e32 v91, v231
	v_pk_add_f32 v[2:3], v[2:3], v[88:89]
	v_exp_f32_e32 v92, v232
	v_pk_add_f32 v[236:237], v[48:49], v[0:1] op_sel_hi:[1,0] neg_lo:[0,1] neg_hi:[0,1]
	v_exp_f32_e32 v93, v233
	v_pk_add_f32 v[2:3], v[2:3], v[90:91]
	v_exp_f32_e32 v94, v234
	v_pk_add_f32 v[238:239], v[50:51], v[0:1] op_sel_hi:[1,0] neg_lo:[0,1] neg_hi:[0,1]
	v_exp_f32_e32 v95, v235
	v_pk_add_f32 v[2:3], v[2:3], v[92:93]
	v_exp_f32_e32 v96, v236
	v_pk_add_f32 v[240:241], v[52:53], v[0:1] op_sel_hi:[1,0] neg_lo:[0,1] neg_hi:[0,1]
	v_exp_f32_e32 v97, v237
	v_pk_add_f32 v[2:3], v[2:3], v[94:95]
	v_exp_f32_e32 v98, v238
	v_pk_add_f32 v[242:243], v[54:55], v[0:1] op_sel_hi:[1,0] neg_lo:[0,1] neg_hi:[0,1]
	v_exp_f32_e32 v99, v239
	v_pk_add_f32 v[2:3], v[2:3], v[96:97]
	v_exp_f32_e32 v100, v240
	v_pk_add_f32 v[244:245], v[56:57], v[0:1] op_sel_hi:[1,0] neg_lo:[0,1] neg_hi:[0,1]
	v_exp_f32_e32 v101, v241
	v_pk_add_f32 v[2:3], v[2:3], v[98:99]
	v_exp_f32_e32 v102, v242
	v_pk_add_f32 v[246:247], v[58:59], v[0:1] op_sel_hi:[1,0] neg_lo:[0,1] neg_hi:[0,1]
	v_exp_f32_e32 v103, v243
	v_pk_add_f32 v[2:3], v[2:3], v[100:101]
	v_exp_f32_e32 v104, v244
	v_pk_add_f32 v[248:249], v[60:61], v[0:1] op_sel_hi:[1,0] neg_lo:[0,1] neg_hi:[0,1]
	v_exp_f32_e32 v105, v245
	v_pk_add_f32 v[2:3], v[2:3], v[102:103]
	v_exp_f32_e32 v106, v246
	v_pk_add_f32 v[250:251], v[62:63], v[0:1] op_sel_hi:[1,0] neg_lo:[0,1] neg_hi:[0,1]
	v_exp_f32_e32 v107, v247
	v_pk_add_f32 v[2:3], v[2:3], v[104:105]
	v_exp_f32_e32 v108, v248
	v_exp_f32_e32 v109, v249
	v_pk_add_f32 v[2:3], v[2:3], v[106:107]
	v_exp_f32_e32 v110, v250
	v_exp_f32_e32 v111, v251
	v_pk_add_f32 v[2:3], v[2:3], v[108:109]
	v_exp_f32_e32 v0, v4
	v_pk_add_f32 v[2:3], v[2:3], v[110:111]
	v_cmp_neq_f32_e32 vcc, 1.0, v0
	v_add_f32_e32 v213, v2, v3
	s_cmp_lg_u64 vcc, 0
	v_fmac_f32_e32 v213, v149, v0
	s_cselect_b64 s[0:1], -1, 0

; DI float half_max(float x) { float a, b; half_swap(x, a, b); return fmaxf(a, b); }
; DI float ex2(float x) { return __builtin_amdgcn_exp2f(x); }
; template <bool HAS_O>
; DI void softmax_finish(f32x16 (&S)[2], float mx, float cbias, float& m, float& l, f32x16 (&O)[2]) {
;   mx = half_max(mx);
;   const float mn = (mx > m + 8.f) ? mx : m;
;   const float alpha = ex2(m - mn);
;   m = mn;
;   const float c = mn + cbias;
;   float sum = 0.f;
; #pragma unroll
;   for (int kt2 = 0; kt2 < 2; ++kt2)
; #pragma unroll
;     for (int e = 0; e < 16; ++e) { const float pv = ex2(S[kt2][e] - c); S[kt2][e] = pv; sum += pv; }
;   l = l * alpha + sum;
;   if constexpr (HAS_O) {
;     if (__ballot(alpha != 1.f) != 0ull) {
; template <bool HAS_O>
; DI void softmax_fast(f32x16 (&S)[2], float& m, float& l, f32x16 (&O)[2], bool live) {
;   float mx = S[0][0];
; #pragma unroll
;   for (int kt2 = 0; kt2 < 2; ++kt2)
; #pragma unroll
;     for (int e = 0; e < 16; ++e) mx = fmaxf(mx, S[kt2][e]);
;   softmax_finish<HAS_O>(S, live ? mx : -1e30f, live ? 0.f : 1e30f, m, l, O);
; }
.LBB0_967:
	v_max_f32_e32 v0, v65, v65
	v_max_f32_e32 v2, v64, v64
	v_max_f32_e32 v0, v2, v0
	v_max3_f32 v0, v0, v66, v67
	v_max3_f32 v0, v0, v68, v69
	v_max3_f32 v0, v0, v70, v71
	v_max3_f32 v0, v0, v72, v73
	v_max3_f32 v0, v0, v74, v75
	v_max3_f32 v0, v0, v76, v77
	v_max3_f32 v0, v0, v78, v79
	v_max3_f32 v0, v0, v48, v49
	v_max3_f32 v0, v0, v50, v51
	v_max3_f32 v0, v0, v52, v53
	v_max3_f32 v0, v0, v54, v55
	v_max3_f32 v0, v0, v56, v57
	v_max3_f32 v0, v0, v58, v59
	v_max3_f32 v0, v0, v60, v61
	v_max3_f32 v0, v0, v62, v63
	v_mov_b32_e32 v2, v0
	s_nop 1
	v_permlane32_swap_b32_e32 v0, v2
	v_max_f32_e32 v2, v2, v2
	v_max_f32_e32 v0, v0, v0
	v_max_f32_e32 v0, v0, v2
	v_add_f32_e32 v2, 0x41000000, v209
	v_cmp_gt_f32_e32 vcc, v0, v2
	s_nop 1
	v_cndmask_b32_e32 v208, v209, v0, vcc
	v_add_f32_e32 v0, 0, v208
	v_pk_add_f32 v[220:221], v[64:65], v[0:1] op_sel_hi:[1,0] neg_lo:[0,1] neg_hi:[0,1]
	v_pk_add_f32 v[222:223], v[66:67], v[0:1] op_sel_hi:[1,0] neg_lo:[0,1] neg_hi:[0,1]
	v_sub_f32_e32 v4, v209, v208
	v_exp_f32_e32 v80, v220
	v_pk_add_f32 v[224:225], v[68:69], v[0:1] op_sel_hi:[1,0] neg_lo:[0,1] neg_hi:[0,1]
	v_exp_f32_e32 v81, v221
	v_exp_f32_e32 v82, v222
	v_pk_add_f32 v[226:227], v[70:71], v[0:1] op_sel_hi:[1,0] neg_lo:[0,1] neg_hi:[0,1]
	v_exp_f32_e32 v83, v223
	v_exp_f32_e32 v84, v224
	v_pk_add_f32 v[228:229], v[72:73], v[0:1] op_sel_hi:[1,0] neg_lo:[0,1] neg_hi:[0,1]
	v_exp_f32_e32 v85, v225
	v_pk_add_f32 v[2:3], v[80:81], v[82:83]
	v_exp_f32_e32 v86, v226
	v_pk_add_f32 v[230:231], v[74:75], v[0:1] op_sel_hi:[1,0] neg_lo:[0,1] neg_hi:[0,1]
	v_exp_f32_e32 v87, v227
	v_pk_add_f32 v[2:3], v[2:3], v[84:85]
	v_exp_f32_e32 v88, v228
	v_pk_add_f32 v[232:233], v[76:77], v[0:1] op_sel_hi:[1,0] neg_lo:[0,1] neg_hi:[0,1]
	v_exp_f32_e32 v89, v229
	v_pk_add_f32 v[2:3], v[2:3], v[86:87]
	v_exp_f32_e32 v90, v230
	v_pk_add_f32 v[234:235], v[78:79], v[0:1] op_sel_hi:[1,0] neg_lo:[0,1] neg_hi:[0,1]
	v_exp_f32_e32 v91, v231
	v_pk_add_f32 v[2:3], v[2:3], v[88:89]
	v_exp_f32_e32 v92, v232
	v_pk_add_f32 v[236:237], v[48:49], v[0:1] op_sel_hi:[1,0] neg_lo:[0,1] neg_hi:[0,1]
	v_exp_f32_e32 v93, v233
	v_pk_add_f32 v[2:3], v[2:3], v[90:91]
	v_exp_f32_e32 v94, v234
	v_pk_add_f32 v[238:239], v[50:51], v[0:1] op_sel_hi:[1,0] neg_lo:[0,1] neg_hi:[0,1]
	v_exp_f32_e32 v95, v235
	v_pk_add_f32 v[2:3], v[2:3], v[92:93]
	v_exp_f32_e32 v96, v236
	v_pk_add_f32 v[240:241], v[52:53], v[0:1] op_sel_hi:[1,0] neg_lo:[0,1] neg_hi:[0,1]
	v_exp_f32_e32 v97, v237
	v_pk_add_f32 v[2:3], v[2:3], v[94:95]
	v_exp_f32_e32 v98, v238
	v_pk_add_f32 v[242:243], v[54:55], v[0:1] op_sel_hi:[1,0] neg_lo:[0,1] neg_hi:[0,1]
	v_exp_f32_e32 v99, v239
	v_pk_add_f32 v[2:3], v[2:3], v[96:97]
	v_exp_f32_e32 v100, v240
	v_pk_add_f32 v[244:245], v[56:57], v[0:1] op_sel_hi:[1,0] neg_lo:[0,1] neg_hi:[0,1]
	v_exp_f32_e32 v101, v241
	v_pk_add_f32 v[2:3], v[2:3], v[98:99]
	v_exp_f32_e32 v102, v242
	v_pk_add_f32 v[246:247], v[58:59], v[0:1] op_sel_hi:[1,0] neg_lo:[0,1] neg_hi:[0,1]
	v_exp_f32_e32 v103, v243
	v_pk_add_f32 v[2:3], v[2:3], v[100:101]
	v_exp_f32_e32 v104, v244
	v_pk_add_f32 v[248:249], v[60:61], v[0:1] op_sel_hi:[1,0] neg_lo:[0,1] neg_hi:[0,1]
	v_exp_f32_e32 v105, v245
	v_pk_add_f32 v[2:3], v[2:3], v[102:103]
	v_exp_f32_e32 v106, v246
	v_pk_add_f32 v[250:251], v[62:63], v[0:1] op_sel_hi:[1,0] neg_lo:[0,1] neg_hi:[0,1]
	v_exp_f32_e32 v107, v247
	v_pk_add_f32 v[2:3], v[2:3], v[104:105]
	v_exp_f32_e32 v108, v248
	v_exp_f32_e32 v109, v249
	v_pk_add_f32 v[2:3], v[2:3], v[106:107]
	v_exp_f32_e32 v110, v250
	v_exp_f32_e32 v111, v251
	v_pk_add_f32 v[2:3], v[2:3], v[108:109]
	v_exp_f32_e32 v0, v4
	v_pk_add_f32 v[2:3], v[2:3], v[110:111]
	v_cmp_neq_f32_e32 vcc, 1.0, v0
	v_add_f32_e32 v149, v2, v3
	s_cmp_lg_u64 vcc, 0
	v_fmac_f32_e32 v149, v213, v0
	s_cselect_b64 s[0:1], -1, 0

; DI float half_max(float x) { float a, b; half_swap(x, a, b); return fmaxf(a, b); }
; DI int crow(int reg, int hh) { return (reg & 3) + 8 * (reg >> 2) + 4 * hh; }
; DI float ex2(float x) { return __builtin_amdgcn_exp2f(x); }
; template <bool HAS_O>
; DI void softmax_finish(f32x16 (&S)[2], float mx, float cbias, float& m, float& l, f32x16 (&O)[2]) {
;   mx = half_max(mx);
;   const float mn = (mx > m + 8.f) ? mx : m;
;   const float alpha = ex2(m - mn);
;   m = mn;
;   const float c = mn + cbias;
;   float sum = 0.f;
; #pragma unroll
;   for (int kt2 = 0; kt2 < 2; ++kt2)
; #pragma unroll
;     for (int e = 0; e < 16; ++e) { const float pv = ex2(S[kt2][e] - c); S[kt2][e] = pv; sum += pv; }
;   l = l * alpha + sum;
;   if constexpr (HAS_O) {
;     if (__ballot(alpha != 1.f) != 0ull) {
; #pragma unroll
;       for (int dt = 0; dt < 2; ++dt)
; #pragma unroll
;         for (int e = 0; e < 16; ++e) O[dt][e] *= alpha;
;     }
;   }
; }
; template <bool HAS_O, class MaskF>
; DI void softmax_step(f32x16 (&S)[2], float& m, float& l, f32x16 (&O)[2], int hh, MaskF mask) {
;   float mx = -1e30f;
; #pragma unroll
;   for (int kt2 = 0; kt2 < 2; ++kt2)
; #pragma unroll
;     for (int e = 0; e < 16; ++e) {
;       const float sv = mask(kt2 * 32 + crow(e, hh)) ? S[kt2][e] : -1e30f;
;       S[kt2][e] = sv; mx = fmaxf(mx, sv);
;     }
;   softmax_finish<HAS_O>(S, mx, 0.f, m, l, O);
; }
; template <bool HAS_O>
; DI void softmax_fast(f32x16 (&S)[2], float& m, float& l, f32x16 (&O)[2], bool live) {
;   float mx = S[0][0];
; #pragma unroll
;   for (int kt2 = 0; kt2 < 2; ++kt2)
; #pragma unroll
;     for (int e = 0; e < 16; ++e) mx = fmaxf(mx, S[kt2][e]);
;   softmax_finish<HAS_O>(S, live ? mx : -1e30f, live ? 0.f : 1e30f, m, l, O);
; }
.LBB0_971:
	s_andn2_b64 vcc, exec, s[34:35]
	s_cbranch_vccnz .LBB0_973
	v_max_f32_e32 v0, v65, v65
	v_max_f32_e32 v3, v64, v64
	v_max_f32_e32 v0, v3, v0
	v_max3_f32 v0, v0, v66, v67
	v_max3_f32 v0, v0, v68, v69
	v_max3_f32 v0, v0, v70, v71
	v_max3_f32 v0, v0, v72, v73
	v_max3_f32 v0, v0, v74, v75
	v_max3_f32 v0, v0, v76, v77
	v_max3_f32 v0, v0, v78, v79
	v_max3_f32 v0, v0, v48, v49
	v_max3_f32 v0, v0, v50, v51
	v_max3_f32 v0, v0, v52, v53
	v_max3_f32 v0, v0, v54, v55
	v_max3_f32 v0, v0, v56, v57
	v_max3_f32 v0, v0, v58, v59
	v_max3_f32 v0, v0, v60, v61
	v_max3_f32 v0, v0, v62, v63
	v_cndmask_b32_e64 v0, v0, v185, s[40:41]
	v_mov_b32_e32 v4, v0
	s_nop 1
	v_permlane32_swap_b32_e32 v0, v4
	v_max_f32_e32 v4, v4, v4
	v_max_f32_e32 v0, v0, v0
	v_max_f32_e32 v0, v0, v4
	v_cmp_gt_f32_e32 vcc, v0, v2
	v_cndmask_b32_e64 v3, 0, v190, s[40:41]
	s_nop 0
	v_cndmask_b32_e32 v208, v209, v0, vcc
	v_add_f32_e32 v0, v3, v208
	v_pk_add_f32 v[220:221], v[64:65], v[0:1] op_sel_hi:[1,0] neg_lo:[0,1] neg_hi:[0,1]
	v_pk_add_f32 v[222:223], v[66:67], v[0:1] op_sel_hi:[1,0] neg_lo:[0,1] neg_hi:[0,1]
	v_sub_f32_e32 v4, v209, v208
	v_exp_f32_e32 v80, v220
	v_pk_add_f32 v[224:225], v[68:69], v[0:1] op_sel_hi:[1,0] neg_lo:[0,1] neg_hi:[0,1]
	v_exp_f32_e32 v81, v221
	v_exp_f32_e32 v82, v222
	v_pk_add_f32 v[226:227], v[70:71], v[0:1] op_sel_hi:[1,0] neg_lo:[0,1] neg_hi:[0,1]
	v_exp_f32_e32 v83, v223
	v_exp_f32_e32 v84, v224
	v_pk_add_f32 v[228:229], v[72:73], v[0:1] op_sel_hi:[1,0] neg_lo:[0,1] neg_hi:[0,1]
	v_exp_f32_e32 v85, v225
	v_pk_add_f32 v[2:3], v[80:81], v[82:83]
	v_exp_f32_e32 v86, v226
	v_pk_add_f32 v[230:231], v[74:75], v[0:1] op_sel_hi:[1,0] neg_lo:[0,1] neg_hi:[0,1]
	v_exp_f32_e32 v87, v227
	v_pk_add_f32 v[2:3], v[2:3], v[84:85]
	v_exp_f32_e32 v88, v228
	v_pk_add_f32 v[232:233], v[76:77], v[0:1] op_sel_hi:[1,0] neg_lo:[0,1] neg_hi:[0,1]
	v_exp_f32_e32 v89, v229
	v_pk_add_f32 v[2:3], v[2:3], v[86:87]
	v_exp_f32_e32 v90, v230
	v_pk_add_f32 v[234:235], v[78:79], v[0:1] op_sel_hi:[1,0] neg_lo:[0,1] neg_hi:[0,1]
	v_exp_f32_e32 v91, v231
	v_pk_add_f32 v[2:3], v[2:3], v[88:89]
	v_exp_f32_e32 v92, v232
	v_pk_add_f32 v[236:237], v[48:49], v[0:1] op_sel_hi:[1,0] neg_lo:[0,1] neg_hi:[0,1]
	v_exp_f32_e32 v93, v233
	v_pk_add_f32 v[2:3], v[2:3], v[90:91]
	v_exp_f32_e32 v94, v234
	v_pk_add_f32 v[238:239], v[50:51], v[0:1] op_sel_hi:[1,0] neg_lo:[0,1] neg_hi:[0,1]
	v_exp_f32_e32 v95, v235
	v_pk_add_f32 v[2:3], v[2:3], v[92:93]
	v_exp_f32_e32 v96, v236
	v_pk_add_f32 v[240:241], v[52:53], v[0:1] op_sel_hi:[1,0] neg_lo:[0,1] neg_hi:[0,1]
	v_exp_f32_e32 v97, v237
	v_pk_add_f32 v[2:3], v[2:3], v[94:95]
	v_exp_f32_e32 v98, v238
	v_pk_add_f32 v[242:243], v[54:55], v[0:1] op_sel_hi:[1,0] neg_lo:[0,1] neg_hi:[0,1]
	v_exp_f32_e32 v99, v239
	v_pk_add_f32 v[2:3], v[2:3], v[96:97]
	v_exp_f32_e32 v100, v240
	v_pk_add_f32 v[244:245], v[56:57], v[0:1] op_sel_hi:[1,0] neg_lo:[0,1] neg_hi:[0,1]
	v_exp_f32_e32 v101, v241
	v_pk_add_f32 v[2:3], v[2:3], v[98:99]
	v_exp_f32_e32 v102, v242
	v_pk_add_f32 v[246:247], v[58:59], v[0:1] op_sel_hi:[1,0] neg_lo:[0,1] neg_hi:[0,1]
	v_exp_f32_e32 v103, v243
	v_pk_add_f32 v[2:3], v[2:3], v[100:101]
	v_exp_f32_e32 v104, v244
	v_pk_add_f32 v[248:249], v[60:61], v[0:1] op_sel_hi:[1,0] neg_lo:[0,1] neg_hi:[0,1]
	v_exp_f32_e32 v105, v245
	v_pk_add_f32 v[2:3], v[2:3], v[102:103]
	v_exp_f32_e32 v106, v246
	v_pk_add_f32 v[250:251], v[62:63], v[0:1] op_sel_hi:[1,0] neg_lo:[0,1] neg_hi:[0,1]
	v_exp_f32_e32 v107, v247
	v_pk_add_f32 v[2:3], v[2:3], v[104:105]
	v_exp_f32_e32 v108, v248
	v_exp_f32_e32 v109, v249
	v_pk_add_f32 v[2:3], v[2:3], v[106:107]
	v_exp_f32_e32 v110, v250
	v_exp_f32_e32 v111, v251
	v_pk_add_f32 v[2:3], v[2:3], v[108:109]
	v_exp_f32_e32 v0, v4
	v_pk_add_f32 v[2:3], v[2:3], v[110:111]
	v_cmp_neq_f32_e32 vcc, 1.0, v0
	v_add_f32_e32 v149, v2, v3
	s_cmp_lg_u64 vcc, 0
	v_fmac_f32_e32 v149, v213, v0
	s_cselect_b64 s[0:1], -1, 0
